# GLA pass-2 prefetch re-ordered (a1, V rows, then q/k) with re-counted in-order vmcnt waits, on top of pipelined step 4 + hoisted gate loads
# speedup vs baseline: 1.0065x; 1.0002x over previous
; #define TIDX(wv) ((wv) * 64 + lane_id_asm())
; __device__ __forceinline__ int crow(int r,int hi){return (r&3)+8*(r>>2)+4*hi;}
; #define GLDS __attribute__((address_space(3)))
; __device__ __forceinline__ int crow(int r, int hi) { return (r & 3) + 8 * (r >> 2) + 4 * hi; }
; #define GBAR() asm volatile("s_waitcnt lgkmcnt(0)\n\ts_barrier" ::: "memory")
; #define lane lane_id_asm()
; #define tid TIDX(wave)
; template <int MODE> __device__ __forceinline__ void chain(int b, int h, int seg, float* __restrict__ SLOC, float* __restrict__ DTOT, const bf16_t* __restrict__ QB, const bf16_t* __restrict__ KB, const bf16_t* __restrict__ VB, bf16_t* __restrict__ OB, const bf16_t* __restrict__ RB, const float* __res ...
;     const int tid = TIDX(wv), lane = tid & 63, wid = wv, hi = lane >> 5, r32 = lane & 31;
;     const ldsp L = (ldsp)shm;
;     GLDS float* W2 = (GLDS float*)(L + W2_OFF); GLDS float* SEG = (GLDS float*)(L + SEG_OFF); GLDS float* EBL = (GLDS float*)(L + EBL_OFF); GLDS float* SSQ = (GLDS float*)(L + SSQ_OFF);
;     for (int i = tid; i < 2048; i += 512) W2[i] = w_a2[(i >> 7) * 512 + h * 128 + (i & 127)];
;     const int c0 = 2 * lane;
;     const float ba0 = b_a2[h * 128 + c0], ba1 = b_a2[h * 128 + c0 + 1];
;     GLDS float* GVL = (GLDS float*)(L + GV_OFF);
;     if (tid < 256) GVL[tid] = g_gla[h * 256 + tid];
;     f32x16 S[4];
; #pragma unroll
;     for (int i = 0; i < 4; ++i) S[i] = f32x16{};
;     const long row00 = (long)b * TSEQ + (long)seg * 1024;
;     float dt0 = 0.f, dt1 = 0.f;
;     if (MODE == 1) {
;         for (int g = 0; g < seg; ++g) { const float* sl = SLOC + ((size_t)((b * 4 + h) * 8 + g) * 128) * 256; const float* dd = DTOT + ((b * 4 + h) * 8 + g) * 128;
; #pragma unroll
;             for (int cb = 0; cb < 4; ++cb)
; #pragma unroll
;                 for (int r = 0; r < 16; ++r) { const int c = 32 * cb + crow(r, hi); S[cb][r] = __expf(dd[c]) * S[cb][r] + sl[(size_t)c * 256 + 32 * wid + r32]; } }
;     }
;     unsigned q2[8], k2[8]; float a1r0, a1r1; u32x4 vr[4];
;     const unsigned lo4 = (unsigned)lane * 4u, lov = (unsigned)(lane >> 5) * 2048u + (unsigned)(lane & 31) * 16u, lor = (unsigned)r32 * 2048u + (unsigned)hi * 8u;
;     ...
;     GLA_LOAD(row00);
;     GBAR();
.LBB0_672:
	s_and_b32 s8, s54, 7
	s_ashr_i32 s93, s92, 31
	s_lshl_b32 s12, s8, 13
	s_lshl_b64 s[4:5], s[92:93], 10
	s_add_u32 s27, s4, s12
	s_addc_u32 s36, s5, 0
	s_and_b32 s4, s23, 3
	s_lshl_b32 s13, s8, 24
	s_lshl_b32 s26, s4, 9
	s_lshl_b32 s12, s8, 23
	s_lshl_b32 s5, s4, 8
	s_lshl_b32 s4, s8, 19
	s_add_u32 s28, s27, s90
	s_addc_u32 s29, s36, 0
	s_lshl_b64 s[30:31], s[28:29], 10
	s_add_u32 s34, s70, s30
	s_addc_u32 s35, s71, s31
	s_lshl_b32 s37, s25, 1
	s_add_u32 s34, s34, s37
	s_addc_u32 s35, s35, 0
	s_add_u32 s30, s6, s30
	s_addc_u32 s31, s7, s31
	s_add_u32 s30, s30, s37
	v_lshlrev_b32_e32 v2, 2, v87
	s_addc_u32 s31, s31, 0
	v_lshlrev_b32_e32 v4, 4, v83
	v_lshl_add_u64 v[8:9], s[30:31], 0, v[2:3]
	s_mov_b64 s[30:31], 0x1b500000
	v_lshl_or_b32 v84, v137, 11, v4
	v_lshl_add_u64 v[4:5], s[34:35], 0, v[2:3]
	s_mov_b64 s[34:35], 0x17400000
	v_lshl_add_u64 v[10:11], v[8:9], 0, s[30:31]
	s_mov_b32 s30, 0x17401000
	v_lshl_add_u64 v[6:7], v[4:5], 0, s[34:35]
	v_add_co_u32_e32 v4, vcc, s30, v4
	s_lshl_b64 s[28:29], s[28:29], 6
	s_nop 0
	v_addc_co_u32_e32 v5, vcc, 0, v5, vcc
	s_mov_b32 s30, 0x1b501000
	s_add_u32 s28, s74, s28
	v_add_co_u32_e32 v8, vcc, s30, v8
	s_addc_u32 s29, s75, s29
	s_nop 0
	v_addc_co_u32_e32 v9, vcc, 0, v9, vcc
	global_load_dword v139, v[6:7], off offset:1024
	global_load_dword v149, v[6:7], off offset:2048
	global_load_dword v150, v[6:7], off offset:3072
	global_load_dword v151, v[10:11], off offset:1024
	global_load_dword v152, v[10:11], off offset:2048
	global_load_dword v153, v[10:11], off offset:3072
	global_load_dword v148, v[4:5], off offset:-4096
	global_load_dword v155, v[4:5], off
	global_load_dword v156, v[4:5], off offset:1024
	global_load_dword v157, v[4:5], off offset:2048
	global_load_dword v158, v[4:5], off offset:3072
	global_load_dword v154, v[8:9], off offset:-4096
	global_load_dword v159, v[8:9], off
	global_load_dword v160, v[8:9], off offset:1024
	global_load_dword v161, v[8:9], off offset:2048
	global_load_dword v162, v[8:9], off offset:3072
	v_lshl_add_u64 v[4:5], s[28:29], 0, v[2:3]
	s_mov_b64 s[28:29], 0x2800000
	v_lshl_add_u64 v[6:7], v[4:5], 0, s[28:29]
	s_mov_b32 s28, 0x2800000
	v_add_co_u32_e32 v4, vcc, s28, v4
	v_readlane_b32 s28, v245, 53
	s_add_u32 s28, s27, s28
	s_addc_u32 s29, s36, 0
	s_lshl_b64 s[28:29], s[28:29], 11
	s_add_u32 s27, s76, s28
	s_addc_u32 s29, s77, s29
	s_lshl_b32 s28, s68, 9
	s_add_u32 s28, s27, s28
	s_addc_u32 s29, s29, 0
	v_mov_b32_e32 v85, v3
	v_addc_co_u32_e32 v5, vcc, 0, v5, vcc
	v_lshl_add_u64 v[12:13], s[28:29], 0, v[84:85]
	s_mov_b32 s27, 0x1f600000
	global_load_dword v165, v[4:5], off
	global_load_dword v166, v[6:7], off offset:256
	v_add_co_u32_e32 v4, vcc, s27, v12
	s_mov_b32 s27, 0x1f608000
	s_nop 0
	v_addc_co_u32_e32 v5, vcc, 0, v13, vcc
	v_add_co_u32_e32 v8, vcc, s27, v12
	s_mov_b32 s27, 0x1f610000
	s_nop 0
	v_addc_co_u32_e32 v9, vcc, 0, v13, vcc
	v_add_co_u32_e32 v14, vcc, s27, v12
	s_mov_b32 s27, 0x1f618000
	s_nop 0
	v_addc_co_u32_e32 v15, vcc, 0, v13, vcc
	v_add_co_u32_e32 v16, vcc, s27, v12
	global_load_dwordx4 v[4:7], v[4:5], off
	s_nop 0
	global_load_dwordx4 v[8:11], v[8:9], off
	v_addc_co_u32_e32 v17, vcc, 0, v13, vcc
	global_load_dwordx4 v[12:15], v[14:15], off
	s_nop 0
	global_load_dwordx4 v[114:117], v[16:17], off
	v_lshlrev_b32_e32 v92, 2, v86
	v_lshlrev_b32_e32 v89, 3, v137
	v_bfe_u32 v17, v86, 2, 2
	v_and_b32_e32 v91, 16, v86
	v_and_b32_e32 v92, 12, v92
	v_readlane_b32 s28, v246, 53
	v_or_b32_e32 v17, v89, v17
	v_mul_u32_u24_e32 v17, 0x240, v17
	v_or3_b32 v91, v91, v92, s28
	v_lshlrev_b32_e32 v91, 1, v91
	s_mov_b32 s27, 0x19e00
	v_add3_u32 v163, s91, v17, v91
	v_lshlrev_b32_e32 v17, 2, v88
	s_addk_i32 s27, 0x100
	v_add_u32_e32 v167, s27, v17
	v_readlane_b32 s27, v245, 54
	v_add_u32_e32 v170, 0x100, v2
	v_and_b32_e32 v16, 15, v86
	v_add_u32_e32 v168, s27, v17
	v_readlane_b32 s27, v245, 45
	v_lshlrev_b32_e32 v88, 4, v86
	v_and_b32_e32 v93, 48, v86
	v_add_u32_e32 v169, s27, v17
	s_movk_i32 s27, 0x11c
	v_mad_u32_u24 v91, v87, s27, v170
	v_readlane_b32 s27, v246, 14
	v_cmp_gt_u32_e64 s[52:53], 32, v87
	v_lshrrev_b32_e32 v87, 5, v82
	v_add_u32_e32 v171, s27, v17
	v_or_b32_e32 v17, s10, v16
	s_movk_i32 s27, 0x110
	v_or_b32_e32 v16, s11, v16
	v_mul_lo_u32 v92, v17, s27
	v_mad_u32_u24 v94, v16, s27, v146
	s_movk_i32 s27, 0x90
	v_lshrrev_b32_e32 v16, 2, v86
	v_mul_lo_u32 v86, v17, s27
	s_add_i32 s27, s81, 0x100
	v_add_u32_e32 v86, s27, v86
	v_add_u32_e32 v96, s27, v138
	v_readlane_b32 s27, v245, 49
	v_add_u32_e32 v99, 0x200, v82
	v_add_u32_e32 v100, 0x400, v82
	v_add_u32_e32 v172, s27, v136
	v_readlane_b32 s27, v245, 57
	v_add_u32_e32 v82, 0x600, v82
	v_readlane_b32 s29, v246, 54
	v_and_or_b32 v16, v16, 12, s11
	v_add_u32_e32 v173, s27, v136
	s_movk_i32 s27, 0x240
	v_lshrrev_b32_e32 v82, 5, v82
	v_mul_lo_u32 v101, v82, s27
	v_or_b32_e32 v82, 16, v16
	v_readlane_b32 s28, v246, 27
	v_cmp_gt_u32_e64 s[56:57], v82, v17
	v_or_b32_e32 v82, 17, v16
	v_readlane_b32 s29, v246, 28
	s_add_u32 s14, s14, s28
	v_cmp_gt_u32_e64 s[60:61], v82, v17
	v_or_b32_e32 v82, 2, v16
	s_mov_b32 s30, s28
	s_addc_u32 s15, s15, 0
	s_lshl_b64 s[28:29], s[92:93], 21
	v_lshrrev_b32_e32 v99, 5, v99
	v_lshrrev_b32_e32 v100, 5, v100
	v_cmp_gt_u32_e64 s[62:63], v82, v17
	v_or_b32_e32 v82, 18, v16
	s_add_u32 s13, s13, s28
	v_lshlrev_b32_e32 v90, 11, v83
	v_mul_lo_u32 v87, v87, s27
	v_mul_lo_u32 v99, v99, s27
	v_mul_lo_u32 v100, v100, s27
	v_cmp_gt_u32_e64 s[64:65], v82, v17
	v_or_b32_e32 v82, 3, v16
	s_addc_u32 s27, 0, s29
	s_or_b32 s26, s13, s26
	v_lshlrev_b32_e32 v95, 1, v16
	v_cmp_gt_u32_e64 s[54:55], v16, v17
	v_cmp_lt_u32_e64 s[58:59], v16, v17
	v_cmp_gt_u32_e64 s[66:67], v82, v17
	v_or_b32_e32 v16, 19, v16
	v_mul_u32_u24_e32 v102, 0x90, v83
	v_mul_u32_u24_e32 v103, 0x110, v83
	v_or3_b32 v82, v90, v89, s26
	v_mov_b32_e32 v83, s27
	s_add_u32 s13, s6, s72
	v_cmp_gt_u32_e64 s[68:69], v16, v17
	v_lshl_add_u64 v[16:17], s[14:15], 0, v[82:83]
	s_addc_u32 s14, s7, s73
	s_lshl_b64 s[6:7], s[92:93], 20
	s_add_u32 s6, s12, s6
	s_addc_u32 s15, 0, s7
	s_or_b32 s5, s6, s5
	s_add_u32 s6, s13, s5
	s_addc_u32 s7, s14, s15
	s_add_u32 s12, s82, s30
	s_addc_u32 s13, s83, 0
	v_lshl_add_u64 v[140:141], s[12:13], 0, v[82:83]
	v_readlane_b32 s12, v245, 47
	v_readlane_b32 s13, v245, 48
	s_add_u32 s12, s76, s12
	s_addc_u32 s13, s77, s13
	s_add_u32 s12, s12, s26
	s_addc_u32 s13, s13, s27
	v_lshl_add_u64 v[142:143], s[12:13], 0, v[84:85]
	v_readlane_b32 s12, v244, 1
	v_readlane_b32 s13, v244, 2
	s_add_u32 s14, s74, s12
	s_addc_u32 s26, s75, s13
	s_lshl_b64 s[12:13], s[92:93], 16
	s_add_u32 s4, s4, s12
	s_addc_u32 s12, 0, s13
	s_add_u32 s74, s14, s4
	s_addc_u32 s75, s26, s12
	s_add_u32 s4, s70, s72
	s_waitcnt lgkmcnt(0)
	s_barrier
; #define GBAR() asm volatile("s_waitcnt lgkmcnt(0)\n\ts_barrier" ::: "memory")
; #define lane lane_id_asm()
; template <int MODE> __device__ __forceinline__ void chain(int b, int h, int seg, float* __restrict__ SLOC, float* __restrict__ DTOT, const bf16_t* __restrict__ QB, const bf16_t* __restrict__ KB, const bf16_t* __restrict__ VB, bf16_t* __restrict__ OB, const bf16_t* __restrict__ RB, const float* __res ...
;     ...
;     GLA_LOAD(row00);
;     GBAR();
;     const ldsp vtr0 = L + V_OFF + (8 * hi + ((lane & 15) >> 2)) * V_RS + (32 * wid + 16 * ((lane >> 4) & 1) + 4 * (lane & 3)) * 2;
;     for (int n = 0; n < 16; ++n) {
	v_and_b32_e32 v88, 0x1f0, v88
	v_add_u32_e32 v97, 0x100, v89
	s_addc_u32 s12, s71, s73
	v_add_u32_e32 v88, 0x100, v88
	v_add_u32_e32 v92, 0x100, v92
	v_add_u32_e32 v98, v97, v89
	s_add_u32 s76, s4, s5
	v_readlane_b32 s4, v245, 55
	v_add_u32_e32 v164, 0xd000, v163
	s_addc_u32 s77, s12, s15
	s_mov_b64 s[82:83], 0
	v_add_u32_e32 v174, v88, v87
	v_add_u32_e32 v175, v88, v99
	v_add_u32_e32 v176, v88, v100
	v_add_u32_e32 v177, v88, v101
	v_add_u32_e32 v178, s4, v91
	v_add_u32_e32 v179, v92, v93
	v_add_u32_e32 v180, v94, v93
	v_add_u32_e32 v181, v86, v95
	v_add_u32_e32 v182, v96, v102
	v_add_u32_e32 v183, v97, v103
	v_add_u32_e32 v184, v98, v102
	s_waitcnt vmcnt(0)
	s_branch .LBB0_674

; #define GLDS __attribute__((address_space(3)))
; template <int MODE> __device__ __forceinline__ void chain(int b, int h, int seg, float* __restrict__ SLOC, float* __restrict__ DTOT, const bf16_t* __restrict__ QB, const bf16_t* __restrict__ KB, const bf16_t* __restrict__ VB, bf16_t* __restrict__ OB, const bf16_t* __restrict__ RB, const float* __res ...
;     ...
;         {
;             float z0[8], z1[8];
; #pragma unroll
;             for (int i = 0; i < 8; ++i) { z0[i] = ba0; z1[i] = ba1; }
; #pragma unroll
;             for (int r = 0; r < 16; ++r) { const f32x2 w = *(const GLDS f32x2*)(W2 + r * 128 + c0);
; #pragma unroll
;                 for (int i = 0; i < 8; ++i) { const int e = i * 16 + r; const float a = __uint_as_float(__builtin_amdgcn_readlane(__float_as_uint(e < 64 ? a1r0 : a1r1), e & 63)); z0[i] += a * w.x; z1[i] += a * w.y; } }
.LBB0_674:
	ds_read2st64_b64 v[98:101], v167 offset1:1
	s_waitcnt vmcnt(29)
	v_readlane_b32 s4, v165, 0
	v_readlane_b32 s5, v165, 7
	v_readlane_b32 s12, v165, 22
	v_readlane_b32 s13, v165, 23
	s_waitcnt lgkmcnt(0)
	v_fma_f32 v97, s4, v98, v134
	v_fma_f32 v94, s4, v99, v135
	v_readlane_b32 s4, v165, 16
	v_readlane_b32 s14, v165, 38
	v_readlane_b32 s15, v165, 39
	v_fma_f32 v96, s4, v98, v134
	v_fma_f32 v95, s4, v99, v135
	v_readlane_b32 s4, v165, 32
	v_readlane_b32 s26, v165, 54
	v_readlane_b32 s27, v165, 55
	v_fma_f32 v93, s4, v98, v134
	v_fma_f32 v92, s4, v99, v135
	v_readlane_b32 s4, v165, 48
	s_waitcnt vmcnt(28)
	v_readlane_b32 s28, v166, 6
	v_readlane_b32 s29, v166, 7
	v_fma_f32 v91, s4, v98, v134
	v_fma_f32 v90, s4, v99, v135
	v_readlane_b32 s4, v166, 0
	v_readlane_b32 s30, v166, 22
	v_readlane_b32 s31, v166, 23
	v_fma_f32 v89, s4, v98, v134
	v_fma_f32 v88, s4, v99, v135
	v_readlane_b32 s4, v166, 16
	v_readlane_b32 s34, v166, 38
	v_readlane_b32 s35, v166, 39
	v_fma_f32 v87, s4, v98, v134
	v_fma_f32 v86, s4, v99, v135
	v_readlane_b32 s4, v166, 32
	v_readlane_b32 s36, v166, 54
	v_readlane_b32 s37, v166, 55
	v_fma_f32 v85, s4, v98, v134
	v_fma_f32 v84, s4, v99, v135
	v_readlane_b32 s4, v166, 48
	s_nop 1
	v_fma_f32 v83, s4, v98, v134
	v_fma_f32 v82, s4, v99, v135
	v_readlane_b32 s4, v165, 1
	s_nop 1
	v_fmac_f32_e32 v97, s4, v100
	v_fmac_f32_e32 v94, s4, v101
	v_readlane_b32 s4, v165, 17
	s_nop 1
	v_fmac_f32_e32 v96, s4, v100
	v_fmac_f32_e32 v95, s4, v101
	v_readlane_b32 s4, v165, 33
	s_nop 1
	v_fmac_f32_e32 v93, s4, v100
	v_fmac_f32_e32 v92, s4, v101
	v_readlane_b32 s4, v165, 49
	s_nop 1
	v_fmac_f32_e32 v91, s4, v100
	v_fmac_f32_e32 v90, s4, v101
	v_readlane_b32 s4, v166, 1
	s_nop 1
	v_fmac_f32_e32 v89, s4, v100
	v_fmac_f32_e32 v88, s4, v101
	v_readlane_b32 s4, v166, 17
	s_nop 1
	v_fmac_f32_e32 v87, s4, v100
	v_fmac_f32_e32 v86, s4, v101
	v_readlane_b32 s4, v166, 33
	s_nop 1
	v_fmac_f32_e32 v85, s4, v100
	v_fmac_f32_e32 v84, s4, v101
	v_readlane_b32 s4, v166, 49
	s_nop 1
	v_fmac_f32_e32 v83, s4, v100
	v_fmac_f32_e32 v82, s4, v101
	ds_read2st64_b64 v[98:101], v167 offset0:2 offset1:3
	v_readlane_b32 s4, v165, 2
	s_waitcnt lgkmcnt(0)
	s_nop 0
	v_fmac_f32_e32 v97, s4, v98
	v_fmac_f32_e32 v94, s4, v99
	v_readlane_b32 s4, v165, 18
	s_nop 1
	v_fmac_f32_e32 v96, s4, v98
	v_fmac_f32_e32 v95, s4, v99
	v_readlane_b32 s4, v165, 34
	s_nop 1
	v_fmac_f32_e32 v93, s4, v98
	v_fmac_f32_e32 v92, s4, v99
	v_readlane_b32 s4, v165, 50
	s_nop 1
	v_fmac_f32_e32 v91, s4, v98
	v_fmac_f32_e32 v90, s4, v99
	v_readlane_b32 s4, v166, 2
	s_nop 1
	v_fmac_f32_e32 v89, s4, v98
	v_fmac_f32_e32 v88, s4, v99
	v_readlane_b32 s4, v166, 18
	s_nop 1
	v_fmac_f32_e32 v87, s4, v98
	v_fmac_f32_e32 v86, s4, v99
	v_readlane_b32 s4, v166, 34
	s_nop 1
	v_fmac_f32_e32 v85, s4, v98
	v_fmac_f32_e32 v84, s4, v99
	v_readlane_b32 s4, v166, 50
	s_nop 1
	v_fmac_f32_e32 v83, s4, v98
	v_fmac_f32_e32 v82, s4, v99
	v_readlane_b32 s4, v165, 3
	s_nop 1
	v_fmac_f32_e32 v97, s4, v100
	v_fmac_f32_e32 v94, s4, v101
	v_readlane_b32 s4, v165, 19
	s_nop 1
	v_fmac_f32_e32 v96, s4, v100
	v_fmac_f32_e32 v95, s4, v101
	v_readlane_b32 s4, v165, 35
	s_nop 1
	v_fmac_f32_e32 v93, s4, v100
	v_fmac_f32_e32 v92, s4, v101
	v_readlane_b32 s4, v165, 51
	s_nop 1
	v_fmac_f32_e32 v91, s4, v100
	v_fmac_f32_e32 v90, s4, v101
	v_readlane_b32 s4, v166, 3
	s_nop 1
	v_fmac_f32_e32 v89, s4, v100
	v_fmac_f32_e32 v88, s4, v101
	v_readlane_b32 s4, v166, 19
	s_nop 1
	v_fmac_f32_e32 v87, s4, v100
	v_fmac_f32_e32 v86, s4, v101
	v_readlane_b32 s4, v166, 35
	s_nop 1
	v_fmac_f32_e32 v85, s4, v100
	v_fmac_f32_e32 v84, s4, v101
	v_readlane_b32 s4, v166, 51
	s_nop 1
	v_fmac_f32_e32 v83, s4, v100
	v_fmac_f32_e32 v82, s4, v101
	ds_read2st64_b64 v[98:101], v167 offset0:4 offset1:5
	v_readlane_b32 s4, v165, 4
	s_waitcnt lgkmcnt(0)
	s_nop 0
	v_fmac_f32_e32 v97, s4, v98
	v_fmac_f32_e32 v94, s4, v99
	v_readlane_b32 s4, v165, 20
	s_nop 1
	v_fmac_f32_e32 v96, s4, v98
	v_fmac_f32_e32 v95, s4, v99
	v_readlane_b32 s4, v165, 36
	s_nop 1
	v_fmac_f32_e32 v93, s4, v98
	v_fmac_f32_e32 v92, s4, v99
	v_readlane_b32 s4, v165, 52
	s_nop 1
	v_fmac_f32_e32 v91, s4, v98
	v_fmac_f32_e32 v90, s4, v99
	v_readlane_b32 s4, v166, 4
	s_nop 1
	v_fmac_f32_e32 v89, s4, v98
	v_fmac_f32_e32 v88, s4, v99
	v_readlane_b32 s4, v166, 20
	s_nop 1
	v_fmac_f32_e32 v87, s4, v98
	v_fmac_f32_e32 v86, s4, v99
	v_readlane_b32 s4, v166, 36
	s_nop 1
	v_fmac_f32_e32 v85, s4, v98
	v_fmac_f32_e32 v84, s4, v99
	v_readlane_b32 s4, v166, 52
	s_nop 1
	v_fmac_f32_e32 v83, s4, v98
	v_fmac_f32_e32 v82, s4, v99
	v_readlane_b32 s4, v165, 5
	s_nop 1
	v_fmac_f32_e32 v97, s4, v100
	v_fmac_f32_e32 v94, s4, v101
	v_readlane_b32 s4, v165, 21
	s_nop 1
	v_fmac_f32_e32 v96, s4, v100
	v_fmac_f32_e32 v95, s4, v101
	v_readlane_b32 s4, v165, 37
	s_nop 1
	v_fmac_f32_e32 v93, s4, v100
	v_fmac_f32_e32 v92, s4, v101
	v_readlane_b32 s4, v165, 53
	s_nop 1
	v_fmac_f32_e32 v91, s4, v100
	v_fmac_f32_e32 v90, s4, v101
	v_readlane_b32 s4, v166, 5
	s_nop 1
	v_fmac_f32_e32 v89, s4, v100
	v_fmac_f32_e32 v88, s4, v101
	v_readlane_b32 s4, v166, 21
	s_nop 1
	v_fmac_f32_e32 v87, s4, v100
	v_fmac_f32_e32 v86, s4, v101
	v_readlane_b32 s4, v166, 37
	s_nop 1
	v_fmac_f32_e32 v85, s4, v100
	v_fmac_f32_e32 v84, s4, v101
	v_readlane_b32 s4, v166, 53
	s_nop 1
	v_fmac_f32_e32 v83, s4, v100
	v_fmac_f32_e32 v82, s4, v101
	ds_read2st64_b64 v[98:101], v167 offset0:6 offset1:7
	v_readlane_b32 s4, v165, 6
	s_waitcnt lgkmcnt(0)
; #define GLDS __attribute__((address_space(3)))
; template <int MODE> __device__ __forceinline__ void chain(int b, int h, int seg, float* __restrict__ SLOC, float* __restrict__ DTOT, const bf16_t* __restrict__ QB, const bf16_t* __restrict__ KB, const bf16_t* __restrict__ VB, bf16_t* __restrict__ OB, const bf16_t* __restrict__ RB, const float* __res ...
;     ...
;             for (int r = 0; r < 16; ++r) { const f32x2 w = *(const GLDS f32x2*)(W2 + r * 128 + c0);
; #pragma unroll
;                 for (int i = 0; i < 8; ++i) { const int e = i * 16 + r; const float a = __uint_as_float(__builtin_amdgcn_readlane(__float_as_uint(e < 64 ? a1r0 : a1r1), e & 63)); z0[i] += a * w.x; z1[i] += a * w.y; } }
	v_mov_b32_e32 v102, v98
	v_mov_b32_e32 v103, v100
	v_mov_b32_e32 v100, v99
	v_pk_mul_f32 v[104:105], v[102:103], s[4:5]
	v_pk_mul_f32 v[98:99], v[100:101], s[4:5]
	v_add_f32_e32 v97, v97, v104
	v_add_f32_e32 v94, v94, v98
	v_add_f32_e32 v104, v97, v105
	v_add_f32_e32 v105, v94, v99
	v_pk_mul_f32 v[98:99], v[102:103], s[12:13]
	v_readlane_b32 s4, v165, 8
	v_add_f32_e32 v94, v96, v98
	v_pk_mul_f32 v[96:97], v[100:101], s[12:13]
	v_add_f32_e32 v98, v94, v99
	v_add_f32_e32 v94, v95, v96
	v_add_f32_e32 v96, v94, v97
	v_pk_mul_f32 v[94:95], v[102:103], s[14:15]
	v_readlane_b32 s5, v165, 9
	v_add_f32_e32 v93, v93, v94
	v_add_f32_e32 v97, v93, v95
	v_pk_mul_f32 v[94:95], v[100:101], s[14:15]
	v_readlane_b32 s12, v165, 24
	v_add_f32_e32 v92, v92, v94
	v_add_f32_e32 v94, v92, v95
	v_pk_mul_f32 v[92:93], v[102:103], s[26:27]
	v_readlane_b32 s13, v165, 25
	v_add_f32_e32 v91, v91, v92
	v_add_f32_e32 v95, v91, v93
	v_pk_mul_f32 v[92:93], v[100:101], s[26:27]
	v_readlane_b32 s14, v165, 40
	v_add_f32_e32 v90, v90, v92
	v_add_f32_e32 v92, v90, v93
	v_pk_mul_f32 v[90:91], v[102:103], s[28:29]
	v_readlane_b32 s15, v165, 41
	v_add_f32_e32 v89, v89, v90
	v_add_f32_e32 v93, v89, v91
	v_pk_mul_f32 v[90:91], v[100:101], s[28:29]
	v_readlane_b32 s26, v165, 56
	v_add_f32_e32 v88, v88, v90
	v_add_f32_e32 v90, v88, v91
	v_pk_mul_f32 v[88:89], v[102:103], s[30:31]
	v_readlane_b32 s27, v165, 57
	v_add_f32_e32 v87, v87, v88
	v_add_f32_e32 v91, v87, v89
	v_pk_mul_f32 v[88:89], v[100:101], s[30:31]
	v_readlane_b32 s28, v166, 8
	v_add_f32_e32 v86, v86, v88
	v_add_f32_e32 v99, v86, v89
	v_pk_mul_f32 v[86:87], v[102:103], s[34:35]
	v_readlane_b32 s29, v166, 9
	v_add_f32_e32 v85, v85, v86
	v_add_f32_e32 v106, v85, v87
	v_pk_mul_f32 v[86:87], v[100:101], s[34:35]
	v_readlane_b32 s30, v166, 24
	v_add_f32_e32 v84, v84, v86
	v_add_f32_e32 v107, v84, v87
	v_pk_mul_f32 v[84:85], v[102:103], s[36:37]
	v_readlane_b32 s31, v166, 25
	v_add_f32_e32 v83, v83, v84
	v_add_f32_e32 v102, v83, v85
	v_pk_mul_f32 v[84:85], v[100:101], s[36:37]
	v_readlane_b32 s34, v166, 40
	v_add_f32_e32 v82, v82, v84
	v_add_f32_e32 v100, v82, v85
	ds_read2st64_b64 v[82:85], v167 offset0:8 offset1:9
	v_readlane_b32 s35, v166, 41
	v_readlane_b32 s36, v166, 56
	v_readlane_b32 s37, v166, 57
	s_waitcnt lgkmcnt(0)
	v_mov_b32_e32 v86, v82
	v_mov_b32_e32 v87, v84
	v_pk_mul_f32 v[88:89], v[86:87], s[4:5]
	v_mov_b32_e32 v84, v83
	v_add_f32_e32 v82, v104, v88
	v_add_f32_e32 v101, v82, v89
	v_pk_mul_f32 v[82:83], v[84:85], s[4:5]
	v_readlane_b32 s4, v165, 10
	v_add_f32_e32 v82, v105, v82
	v_add_f32_e32 v103, v82, v83
	v_pk_mul_f32 v[82:83], v[86:87], s[12:13]
	v_readlane_b32 s5, v165, 11
	v_add_f32_e32 v82, v98, v82
	v_add_f32_e32 v98, v82, v83
	v_pk_mul_f32 v[82:83], v[84:85], s[12:13]
	v_readlane_b32 s12, v165, 26
	v_add_f32_e32 v82, v96, v82
	v_add_f32_e32 v96, v82, v83
	v_pk_mul_f32 v[82:83], v[86:87], s[14:15]
	v_readlane_b32 s13, v165, 27
	v_add_f32_e32 v82, v97, v82
	v_add_f32_e32 v97, v82, v83
	v_pk_mul_f32 v[82:83], v[84:85], s[14:15]
	v_readlane_b32 s14, v165, 42
	v_add_f32_e32 v82, v94, v82
	v_add_f32_e32 v94, v82, v83
	v_pk_mul_f32 v[82:83], v[86:87], s[26:27]
	v_readlane_b32 s15, v165, 43
	v_add_f32_e32 v82, v95, v82
	v_add_f32_e32 v95, v82, v83
	v_pk_mul_f32 v[82:83], v[84:85], s[26:27]
	v_readlane_b32 s26, v165, 58
	v_add_f32_e32 v82, v92, v82
	v_add_f32_e32 v92, v82, v83
	v_pk_mul_f32 v[82:83], v[86:87], s[28:29]
	v_readlane_b32 s27, v165, 59
	v_add_f32_e32 v82, v93, v82
	v_add_f32_e32 v93, v82, v83
	v_pk_mul_f32 v[82:83], v[84:85], s[28:29]
	v_readlane_b32 s28, v166, 10
	v_add_f32_e32 v82, v90, v82
	v_add_f32_e32 v90, v82, v83
	v_pk_mul_f32 v[82:83], v[86:87], s[30:31]
	v_readlane_b32 s29, v166, 11
	v_add_f32_e32 v82, v91, v82
	v_add_f32_e32 v91, v82, v83
	v_pk_mul_f32 v[82:83], v[84:85], s[30:31]
	v_readlane_b32 s30, v166, 26
	v_add_f32_e32 v82, v99, v82
	v_add_f32_e32 v99, v82, v83
	v_pk_mul_f32 v[82:83], v[86:87], s[34:35]
	v_readlane_b32 s31, v166, 27
	v_add_f32_e32 v82, v106, v82
	v_add_f32_e32 v104, v82, v83
	v_pk_mul_f32 v[82:83], v[84:85], s[34:35]
	v_readlane_b32 s34, v166, 42
	v_add_f32_e32 v82, v107, v82
	v_add_f32_e32 v105, v82, v83
	v_pk_mul_f32 v[82:83], v[86:87], s[36:37]
	v_readlane_b32 s35, v166, 43
	v_add_f32_e32 v82, v102, v82
	v_add_f32_e32 v102, v82, v83
	v_pk_mul_f32 v[82:83], v[84:85], s[36:37]
	v_readlane_b32 s36, v166, 58
	v_add_f32_e32 v82, v100, v82
	v_add_f32_e32 v100, v82, v83
	ds_read2st64_b64 v[82:85], v167 offset0:10 offset1:11
	v_readlane_b32 s37, v166, 59
	s_waitcnt lgkmcnt(0)
; #define GLDS __attribute__((address_space(3)))
; template <int MODE> __device__ __forceinline__ void chain(int b, int h, int seg, float* __restrict__ SLOC, float* __restrict__ DTOT, const bf16_t* __restrict__ QB, const bf16_t* __restrict__ KB, const bf16_t* __restrict__ VB, bf16_t* __restrict__ OB, const bf16_t* __restrict__ RB, const float* __res ...
;     ...
;             for (int r = 0; r < 16; ++r) { const f32x2 w = *(const GLDS f32x2*)(W2 + r * 128 + c0);
; #pragma unroll
;                 for (int i = 0; i < 8; ++i) { const int e = i * 16 + r; const float a = __uint_as_float(__builtin_amdgcn_readlane(__float_as_uint(e < 64 ? a1r0 : a1r1), e & 63)); z0[i] += a * w.x; z1[i] += a * w.y; } }
	v_mov_b32_e32 v86, v82
	v_mov_b32_e32 v87, v84
	v_pk_mul_f32 v[88:89], v[86:87], s[4:5]
	v_mov_b32_e32 v84, v83
	v_add_f32_e32 v82, v101, v88
	v_add_f32_e32 v101, v82, v89
	v_pk_mul_f32 v[82:83], v[84:85], s[4:5]
	v_readlane_b32 s4, v165, 12
	v_add_f32_e32 v82, v103, v82
	v_add_f32_e32 v103, v82, v83
	v_pk_mul_f32 v[82:83], v[86:87], s[12:13]
	v_readlane_b32 s5, v165, 13
	v_add_f32_e32 v82, v98, v82
	v_add_f32_e32 v98, v82, v83
	v_pk_mul_f32 v[82:83], v[84:85], s[12:13]
	v_readlane_b32 s12, v165, 28
	v_add_f32_e32 v82, v96, v82
	v_add_f32_e32 v96, v82, v83
	v_pk_mul_f32 v[82:83], v[86:87], s[14:15]
	v_readlane_b32 s13, v165, 29
	v_add_f32_e32 v82, v97, v82
	v_add_f32_e32 v97, v82, v83
	v_pk_mul_f32 v[82:83], v[84:85], s[14:15]
	v_readlane_b32 s14, v165, 44
	v_add_f32_e32 v82, v94, v82
	v_add_f32_e32 v94, v82, v83
	v_pk_mul_f32 v[82:83], v[86:87], s[26:27]
	v_readlane_b32 s15, v165, 45
	v_add_f32_e32 v82, v95, v82
	v_add_f32_e32 v95, v82, v83
	v_pk_mul_f32 v[82:83], v[84:85], s[26:27]
	v_readlane_b32 s26, v165, 60
	v_add_f32_e32 v82, v92, v82
	v_add_f32_e32 v92, v82, v83
	v_pk_mul_f32 v[82:83], v[86:87], s[28:29]
	v_readlane_b32 s27, v165, 61
	v_add_f32_e32 v82, v93, v82
	v_add_f32_e32 v93, v82, v83
	v_pk_mul_f32 v[82:83], v[84:85], s[28:29]
	v_readlane_b32 s28, v166, 12
	v_add_f32_e32 v82, v90, v82
	v_add_f32_e32 v90, v82, v83
	v_pk_mul_f32 v[82:83], v[86:87], s[30:31]
	v_readlane_b32 s29, v166, 13
	v_add_f32_e32 v82, v91, v82
	v_add_f32_e32 v91, v82, v83
	v_pk_mul_f32 v[82:83], v[84:85], s[30:31]
	v_readlane_b32 s30, v166, 28
	v_add_f32_e32 v82, v99, v82
	v_add_f32_e32 v99, v82, v83
	v_pk_mul_f32 v[82:83], v[86:87], s[34:35]
	v_readlane_b32 s31, v166, 29
	v_add_f32_e32 v82, v104, v82
	v_add_f32_e32 v104, v82, v83
	v_pk_mul_f32 v[82:83], v[84:85], s[34:35]
	v_readlane_b32 s34, v166, 44
	v_add_f32_e32 v82, v105, v82
	v_add_f32_e32 v105, v82, v83
	v_pk_mul_f32 v[82:83], v[86:87], s[36:37]
	v_readlane_b32 s35, v166, 45
	v_add_f32_e32 v82, v102, v82
	v_add_f32_e32 v102, v82, v83
	v_pk_mul_f32 v[82:83], v[84:85], s[36:37]
	v_readlane_b32 s36, v166, 60
	v_add_f32_e32 v82, v100, v82
	v_add_f32_e32 v100, v82, v83
	ds_read2st64_b64 v[82:85], v167 offset0:12 offset1:13
	v_readlane_b32 s37, v166, 61
	s_waitcnt lgkmcnt(0)
	v_mov_b32_e32 v86, v82
	v_mov_b32_e32 v87, v84
	v_pk_mul_f32 v[88:89], v[86:87], s[4:5]
	v_mov_b32_e32 v84, v83
	v_add_f32_e32 v82, v101, v88
	v_add_f32_e32 v101, v82, v89
	v_pk_mul_f32 v[82:83], v[84:85], s[4:5]
	v_readlane_b32 s4, v165, 14
	v_add_f32_e32 v82, v103, v82
	v_add_f32_e32 v103, v82, v83
	v_pk_mul_f32 v[82:83], v[86:87], s[12:13]
	v_readlane_b32 s5, v165, 15
	v_add_f32_e32 v82, v98, v82
	v_add_f32_e32 v98, v82, v83
	v_pk_mul_f32 v[82:83], v[84:85], s[12:13]
	v_readlane_b32 s12, v165, 30
	v_add_f32_e32 v82, v96, v82
	v_add_f32_e32 v96, v82, v83
	v_pk_mul_f32 v[82:83], v[86:87], s[14:15]
	v_readlane_b32 s13, v165, 31
	v_add_f32_e32 v82, v97, v82
	v_add_f32_e32 v97, v82, v83
	v_pk_mul_f32 v[82:83], v[84:85], s[14:15]
	v_readlane_b32 s14, v165, 46
	v_add_f32_e32 v82, v94, v82
	v_add_f32_e32 v94, v82, v83
	v_pk_mul_f32 v[82:83], v[86:87], s[26:27]
	v_readlane_b32 s15, v165, 47
	v_add_f32_e32 v82, v95, v82
	v_add_f32_e32 v95, v82, v83
	v_pk_mul_f32 v[82:83], v[84:85], s[26:27]
	v_readlane_b32 s26, v165, 62
	v_add_f32_e32 v82, v92, v82
	v_add_f32_e32 v92, v82, v83
	v_pk_mul_f32 v[82:83], v[86:87], s[28:29]
	v_readlane_b32 s27, v165, 63
	v_add_f32_e32 v82, v93, v82
	v_add_f32_e32 v93, v82, v83
	v_pk_mul_f32 v[82:83], v[84:85], s[28:29]
	v_readlane_b32 s28, v166, 14
	v_add_f32_e32 v82, v90, v82
	v_add_f32_e32 v90, v82, v83
	v_pk_mul_f32 v[82:83], v[86:87], s[30:31]
	v_readlane_b32 s29, v166, 15
	v_add_f32_e32 v82, v91, v82
	v_add_f32_e32 v91, v82, v83
	v_pk_mul_f32 v[82:83], v[84:85], s[30:31]
	v_readlane_b32 s30, v166, 30
	v_add_f32_e32 v82, v99, v82
	v_add_f32_e32 v106, v82, v83
	v_pk_mul_f32 v[82:83], v[86:87], s[34:35]
	v_readlane_b32 s31, v166, 31
	v_add_f32_e32 v82, v104, v82
	v_add_f32_e32 v104, v82, v83
	v_pk_mul_f32 v[82:83], v[84:85], s[34:35]
	v_readlane_b32 s34, v166, 46
	v_add_f32_e32 v82, v105, v82
	v_add_f32_e32 v108, v82, v83
	v_pk_mul_f32 v[82:83], v[86:87], s[36:37]
	v_readlane_b32 s35, v166, 47
	v_add_f32_e32 v82, v102, v82
	v_add_f32_e32 v102, v82, v83
	v_pk_mul_f32 v[82:83], v[84:85], s[36:37]
	v_readlane_b32 s36, v166, 62
	v_add_f32_e32 v82, v100, v82
	v_add_f32_e32 v100, v82, v83
	ds_read2st64_b64 v[82:85], v167 offset0:14 offset1:15
	v_readlane_b32 s37, v166, 63
	s_waitcnt lgkmcnt(0)
; __device__ __forceinline__ float logsig(float z) { return fminf(z, 0.f) - __logf(1.0f + __expf(-fabsf(z))); }
; template <int MODE> __device__ __forceinline__ void chain(int b, int h, int seg, float* __restrict__ SLOC, float* __restrict__ DTOT, const bf16_t* __restrict__ QB, const bf16_t* __restrict__ KB, const bf16_t* __restrict__ VB, bf16_t* __restrict__ OB, const bf16_t* __restrict__ RB, const float* __res ...
;     ...
;                 for (int i = 0; i < 8; ++i) { const int e = i * 16 + r; const float a = __uint_as_float(__builtin_amdgcn_readlane(__float_as_uint(e < 64 ? a1r0 : a1r1), e & 63)); z0[i] += a * w.x; z1[i] += a * w.y; } }
;             float run0 = 0.f, run1 = 0.f;
; #pragma unroll
;             for (int i = 0; i < 8; ++i) { run0 += logsig(z0[i]) * 0.0625f; run1 += logsig(z1[i]) * 0.0625f; bl0[i] = run0; bl1[i] = run1; }
	v_mov_b32_e32 v86, v82
	v_mov_b32_e32 v87, v84
	v_pk_mul_f32 v[88:89], v[86:87], s[4:5]
	v_mov_b32_e32 v84, v83
	v_add_f32_e32 v82, v101, v88
	v_add_f32_e32 v88, v82, v89
	v_pk_mul_f32 v[82:83], v[84:85], s[4:5]
	s_nop 0
	v_add_f32_e32 v82, v103, v82
	v_add_f32_e32 v89, v82, v83
	v_pk_mul_f32 v[82:83], v[86:87], s[12:13]
	s_nop 0
	v_add_f32_e32 v82, v98, v82
	v_add_f32_e32 v98, v82, v83
	v_pk_mul_f32 v[82:83], v[84:85], s[12:13]
	s_nop 0
	v_add_f32_e32 v82, v96, v82
	v_add_f32_e32 v96, v82, v83
	v_pk_mul_f32 v[82:83], v[86:87], s[14:15]
	s_nop 0
	v_add_f32_e32 v82, v97, v82
	v_add_f32_e32 v110, v82, v83
	v_pk_mul_f32 v[82:83], v[84:85], s[14:15]
	s_nop 0
	v_add_f32_e32 v82, v94, v82
	v_add_f32_e32 v94, v82, v83
	v_pk_mul_f32 v[82:83], v[86:87], s[26:27]
	s_nop 0
	v_add_f32_e32 v82, v95, v82
	v_add_f32_e32 v95, v82, v83
	v_pk_mul_f32 v[82:83], v[84:85], s[26:27]
	s_nop 0
	v_add_f32_e32 v82, v92, v82
	v_add_f32_e32 v97, v82, v83
	v_pk_mul_f32 v[82:83], v[86:87], s[28:29]
	s_nop 0
	v_add_f32_e32 v82, v93, v82
	v_add_f32_e32 v99, v82, v83
	v_pk_mul_f32 v[82:83], v[84:85], s[28:29]
	v_mul_f32_e64 v93, |v94|, s18
	v_add_f32_e32 v82, v90, v82
	v_add_f32_e32 v101, v82, v83
	v_pk_mul_f32 v[82:83], v[86:87], s[30:31]
	v_exp_f32_e32 v93, v93
	v_add_f32_e32 v82, v91, v82
	v_add_f32_e32 v105, v82, v83
	v_pk_mul_f32 v[82:83], v[84:85], s[30:31]
	v_mul_f32_e64 v91, |v110|, s18
	v_add_f32_e32 v82, v106, v82
	v_add_f32_e32 v109, v82, v83
	v_pk_mul_f32 v[82:83], v[86:87], s[34:35]
	v_exp_f32_e32 v91, v91
	v_add_f32_e32 v82, v104, v82
	v_add_f32_e32 v107, v82, v83
	v_pk_mul_f32 v[82:83], v[84:85], s[34:35]
	v_add_f32_e32 v91, 1.0, v91
	v_add_f32_e32 v82, v108, v82
	v_add_f32_e32 v106, v82, v83
	v_pk_mul_f32 v[82:83], v[86:87], s[36:37]
	v_mul_f32_e64 v87, |v98|, s18
	v_add_f32_e32 v82, v102, v82
	v_add_f32_e32 v103, v82, v83
	v_pk_mul_f32 v[82:83], v[84:85], s[36:37]
	v_mul_f32_e64 v85, |v89|, s18
	v_add_f32_e32 v82, v100, v82
	v_add_f32_e32 v102, v82, v83
	v_mul_f32_e64 v83, |v88|, s18
	v_exp_f32_e32 v83, v83
	v_exp_f32_e32 v85, v85
	v_exp_f32_e32 v87, v87
	v_min_f32_e32 v82, 0, v88
	v_add_f32_e32 v83, 1.0, v83
	v_cmp_gt_f32_e32 vcc, s21, v83
	v_add_f32_e32 v85, 1.0, v85
	v_add_f32_e32 v87, 1.0, v87
	v_cndmask_b32_e64 v84, 0, 32, vcc
	v_ldexp_f32 v83, v83, v84
	v_log_f32_e32 v83, v83
	v_add_f32_e32 v93, 1.0, v93
	v_min_f32_e32 v120, 0, v103
	v_mul_f32_e64 v103, |v103|, s18
	v_mul_f32_e32 v84, 0x3f317217, v83
	v_fma_f32 v84, v83, s20, -v84
	v_fmac_f32_e32 v84, 0x3377d1cf, v83
	v_fmac_f32_e32 v84, 0x3f317217, v83
	v_cmp_lt_f32_e64 s[70:71], |v83|, s19
	v_exp_f32_e32 v103, v103
	v_min_f32_e32 v121, 0, v102
	v_cndmask_b32_e64 v83, v83, v84, s[70:71]
	v_cndmask_b32_e32 v84, 0, v147, vcc
	v_cmp_gt_f32_e32 vcc, s21, v85
	v_sub_f32_e32 v84, v83, v84
	v_min_f32_e32 v83, 0, v89
	v_cndmask_b32_e64 v86, 0, 32, vcc
	v_ldexp_f32 v85, v85, v86
	v_log_f32_e32 v85, v85
	v_mul_f32_e64 v89, |v96|, s18
	v_exp_f32_e32 v89, v89
	v_add_f32_e32 v103, 1.0, v103
	v_mul_f32_e32 v86, 0x3f317217, v85
	v_fma_f32 v86, v85, s20, -v86
	v_fmac_f32_e32 v86, 0x3377d1cf, v85
	v_fmac_f32_e32 v86, 0x3f317217, v85
	v_cmp_lt_f32_e64 s[70:71], |v85|, s19
	v_add_f32_e32 v89, 1.0, v89
	v_mul_f32_e64 v102, |v102|, s18
	v_cndmask_b32_e64 v85, v85, v86, s[70:71]
	v_cndmask_b32_e32 v86, 0, v147, vcc
	v_cmp_gt_f32_e32 vcc, s21, v87
	v_sub_f32_e32 v85, v85, v86
	v_min_f32_e32 v86, 0, v98
	v_cndmask_b32_e64 v88, 0, 32, vcc
	v_ldexp_f32 v87, v87, v88
	v_log_f32_e32 v87, v87
	v_exp_f32_e32 v102, v102
	v_pk_add_f32 v[82:83], v[82:83], v[84:85] neg_lo:[0,1] neg_hi:[0,1]
	v_mul_f32_e32 v88, 0x3f317217, v87
	v_fma_f32 v88, v87, s20, -v88
	v_fmac_f32_e32 v88, 0x3377d1cf, v87
	v_fmac_f32_e32 v88, 0x3f317217, v87
	v_cmp_lt_f32_e64 s[70:71], |v87|, s19
	v_add_f32_e32 v102, 1.0, v102
	v_pk_fma_f32 v[112:113], v[82:83], s[78:79], 0 op_sel_hi:[1,0,0]
	v_cndmask_b32_e64 v87, v87, v88, s[70:71]
	v_cndmask_b32_e32 v88, 0, v147, vcc
	v_cmp_gt_f32_e32 vcc, s21, v89
	v_sub_f32_e32 v88, v87, v88
	v_min_f32_e32 v87, 0, v96
	v_cndmask_b32_e64 v90, 0, 32, vcc
	v_ldexp_f32 v89, v89, v90
	v_log_f32_e32 v89, v89
	s_nop 0
	v_mul_f32_e32 v90, 0x3f317217, v89
	v_fma_f32 v90, v89, s20, -v90
	v_fmac_f32_e32 v90, 0x3377d1cf, v89
	v_fmac_f32_e32 v90, 0x3f317217, v89
	v_cmp_lt_f32_e64 s[70:71], |v89|, s19
	s_nop 1
	v_cndmask_b32_e64 v89, v89, v90, s[70:71]
	v_cndmask_b32_e32 v90, 0, v147, vcc
	v_cmp_gt_f32_e32 vcc, s21, v91
	v_sub_f32_e32 v89, v89, v90
	v_min_f32_e32 v90, 0, v110
	v_cndmask_b32_e64 v92, 0, 32, vcc
	v_ldexp_f32 v91, v91, v92
	v_log_f32_e32 v91, v91
	v_pk_add_f32 v[82:83], v[86:87], v[88:89] neg_lo:[0,1] neg_hi:[0,1]
	v_mul_f32_e32 v92, 0x3f317217, v91
	v_fma_f32 v92, v91, s20, -v92
	v_fmac_f32_e32 v92, 0x3377d1cf, v91
	v_fmac_f32_e32 v92, 0x3f317217, v91
	v_cmp_lt_f32_e64 s[70:71], |v91|, s19
	v_pk_fma_f32 v[82:83], v[82:83], s[78:79], v[112:113] op_sel_hi:[1,0,1]
	s_nop 0
	v_cndmask_b32_e64 v91, v91, v92, s[70:71]
	v_cndmask_b32_e32 v92, 0, v147, vcc
	v_cmp_gt_f32_e32 vcc, s21, v93
	v_sub_f32_e32 v92, v91, v92
	v_min_f32_e32 v91, 0, v94
	v_cndmask_b32_e64 v94, 0, 32, vcc
	v_ldexp_f32 v93, v93, v94
	v_log_f32_e32 v93, v93
	s_nop 0
	v_mul_f32_e32 v94, 0x3f317217, v93
	v_fma_f32 v94, v93, s20, -v94
	v_fmac_f32_e32 v94, 0x3377d1cf, v93
	v_fmac_f32_e32 v94, 0x3f317217, v93
	v_cmp_lt_f32_e64 s[70:71], |v93|, s19
	s_nop 1
	v_cndmask_b32_e64 v93, v93, v94, s[70:71]
	v_cndmask_b32_e32 v94, 0, v147, vcc
	v_sub_f32_e32 v93, v93, v94
	v_min_f32_e32 v94, 0, v95
	v_mul_f32_e64 v95, |v95|, s18
	v_exp_f32_e32 v95, v95
	v_pk_add_f32 v[84:85], v[90:91], v[92:93] neg_lo:[0,1] neg_hi:[0,1]
	v_add_f32_e32 v95, 1.0, v95
	v_cmp_gt_f32_e32 vcc, s21, v95
; #define GLDS __attribute__((address_space(3)))
; __device__ __forceinline__ float logsig(float z) { return fminf(z, 0.f) - __logf(1.0f + __expf(-fabsf(z))); }
; #define tid TIDX(wave)
; template <int MODE> __device__ __forceinline__ void chain(int b, int h, int seg, float* __restrict__ SLOC, float* __restrict__ DTOT, const bf16_t* __restrict__ QB, const bf16_t* __restrict__ KB, const bf16_t* __restrict__ VB, bf16_t* __restrict__ OB, const bf16_t* __restrict__ RB, const float* __res ...
;     ...
;             for (int i = 0; i < 8; ++i) { run0 += logsig(z0[i]) * 0.0625f; run1 += logsig(z1[i]) * 0.0625f; bl0[i] = run0; bl1[i] = run1; }
;             *(GLDS f32x2*)(SEG + wid * 128 + c0) = (f32x2){run0, run1};
;         }
; #pragma unroll
;         for (int j = 0; j < 4; ++j) { const int idx = j * 512 + tid; *(GLDS u32x4*)(L + V_OFF + (idx >> 5) * V_RS + (idx & 31) * 16) = vr[j]; }
	s_nop 1
	v_cndmask_b32_e64 v96, 0, 32, vcc
	v_ldexp_f32 v95, v95, v96
	v_log_f32_e32 v95, v95
	s_nop 0
	v_mul_f32_e32 v96, 0x3f317217, v95
	v_fma_f32 v96, v95, s20, -v96
	v_fmac_f32_e32 v96, 0x3377d1cf, v95
	v_fmac_f32_e32 v96, 0x3f317217, v95
	v_cmp_lt_f32_e64 s[70:71], |v95|, s19
	s_nop 1
	v_cndmask_b32_e64 v95, v95, v96, s[70:71]
	v_cndmask_b32_e32 v96, 0, v147, vcc
	v_sub_f32_e32 v96, v95, v96
	v_min_f32_e32 v95, 0, v97
	v_mul_f32_e64 v97, |v97|, s18
	v_exp_f32_e32 v97, v97
	s_nop 0
	v_add_f32_e32 v97, 1.0, v97
	v_cmp_gt_f32_e32 vcc, s21, v97
	s_nop 1
	v_cndmask_b32_e64 v98, 0, 32, vcc
	v_ldexp_f32 v97, v97, v98
	v_log_f32_e32 v97, v97
	s_nop 0
	v_mul_f32_e32 v98, 0x3f317217, v97
	v_fma_f32 v98, v97, s20, -v98
	v_fmac_f32_e32 v98, 0x3377d1cf, v97
	v_fmac_f32_e32 v98, 0x3f317217, v97
	v_cmp_lt_f32_e64 s[70:71], |v97|, s19
	s_nop 1
	v_cndmask_b32_e64 v97, v97, v98, s[70:71]
	v_cndmask_b32_e32 v98, 0, v147, vcc
	v_sub_f32_e32 v97, v97, v98
	v_min_f32_e32 v98, 0, v99
	v_mul_f32_e64 v99, |v99|, s18
	v_exp_f32_e32 v99, v99
	s_nop 0
	v_add_f32_e32 v99, 1.0, v99
	v_cmp_gt_f32_e32 vcc, s21, v99
	s_nop 1
	v_cndmask_b32_e64 v100, 0, 32, vcc
	v_ldexp_f32 v99, v99, v100
	v_log_f32_e32 v99, v99
	s_nop 0
	v_mul_f32_e32 v100, 0x3f317217, v99
	v_fma_f32 v100, v99, s20, -v100
	v_fmac_f32_e32 v100, 0x3377d1cf, v99
	v_fmac_f32_e32 v100, 0x3f317217, v99
	v_cmp_lt_f32_e64 s[70:71], |v99|, s19
	s_nop 1
	v_cndmask_b32_e64 v99, v99, v100, s[70:71]
	v_cndmask_b32_e32 v100, 0, v147, vcc
	v_sub_f32_e32 v100, v99, v100
	v_min_f32_e32 v99, 0, v101
	v_mul_f32_e64 v101, |v101|, s18
	v_exp_f32_e32 v101, v101
	s_nop 0
	v_add_f32_e32 v101, 1.0, v101
	v_cmp_gt_f32_e32 vcc, s21, v101
	s_nop 1
	v_cndmask_b32_e64 v104, 0, 32, vcc
	v_ldexp_f32 v101, v101, v104
	v_log_f32_e32 v101, v101
	s_nop 0
	v_mul_f32_e32 v104, 0x3f317217, v101
	v_fma_f32 v104, v101, s20, -v104
	v_fmac_f32_e32 v104, 0x3377d1cf, v101
	v_fmac_f32_e32 v104, 0x3f317217, v101
	v_cmp_lt_f32_e64 s[70:71], |v101|, s19
	s_nop 1
	v_cndmask_b32_e64 v101, v101, v104, s[70:71]
	v_cndmask_b32_e32 v104, 0, v147, vcc
	v_sub_f32_e32 v101, v101, v104
	v_min_f32_e32 v104, 0, v105
	v_mul_f32_e64 v105, |v105|, s18
	v_exp_f32_e32 v105, v105
	s_nop 0
	v_add_f32_e32 v105, 1.0, v105
	v_cmp_gt_f32_e32 vcc, s21, v105
	s_nop 1
	v_cndmask_b32_e64 v108, 0, 32, vcc
	v_ldexp_f32 v105, v105, v108
	v_log_f32_e32 v105, v105
	s_nop 0
	v_mul_f32_e32 v108, 0x3f317217, v105
	v_fma_f32 v108, v105, s20, -v108
	v_fmac_f32_e32 v108, 0x3377d1cf, v105
	v_fmac_f32_e32 v108, 0x3f317217, v105
	v_cmp_lt_f32_e64 s[70:71], |v105|, s19
	s_nop 1
	v_cndmask_b32_e64 v105, v105, v108, s[70:71]
	v_cndmask_b32_e32 v108, 0, v147, vcc
	v_sub_f32_e32 v108, v105, v108
	v_min_f32_e32 v105, 0, v109
	v_mul_f32_e64 v109, |v109|, s18
	v_exp_f32_e32 v109, v109
	s_nop 0
	v_add_f32_e32 v109, 1.0, v109
	v_cmp_gt_f32_e32 vcc, s21, v109
	s_nop 1
	v_cndmask_b32_e64 v110, 0, 32, vcc
	v_ldexp_f32 v109, v109, v110
	v_log_f32_e32 v109, v109
	s_nop 0
	v_mul_f32_e32 v110, 0x3f317217, v109
	v_fma_f32 v110, v109, s20, -v110
	v_fmac_f32_e32 v110, 0x3377d1cf, v109
	v_fmac_f32_e32 v110, 0x3f317217, v109
	v_cmp_lt_f32_e64 s[70:71], |v109|, s19
	s_nop 1
	v_cndmask_b32_e64 v109, v109, v110, s[70:71]
	v_cndmask_b32_e32 v110, 0, v147, vcc
	v_sub_f32_e32 v109, v109, v110
	v_min_f32_e32 v110, 0, v107
	v_mul_f32_e64 v107, |v107|, s18
	v_exp_f32_e32 v107, v107
	s_nop 0
	v_add_f32_e32 v107, 1.0, v107
	v_cmp_gt_f32_e32 vcc, s21, v107
	s_nop 1
	v_cndmask_b32_e64 v111, 0, 32, vcc
	v_ldexp_f32 v107, v107, v111
	v_log_f32_e32 v107, v107
	s_nop 0
	v_mul_f32_e32 v111, 0x3f317217, v107
	v_fma_f32 v111, v107, s20, -v111
	v_fmac_f32_e32 v111, 0x3377d1cf, v107
	v_fmac_f32_e32 v111, 0x3f317217, v107
	v_cmp_lt_f32_e64 s[70:71], |v107|, s19
	s_nop 1
	v_cndmask_b32_e64 v107, v107, v111, s[70:71]
	v_cndmask_b32_e32 v111, 0, v147, vcc
	v_sub_f32_e32 v118, v107, v111
	v_min_f32_e32 v111, 0, v106
	v_mul_f32_e64 v106, |v106|, s18
	v_exp_f32_e32 v106, v106
	s_nop 0
	v_add_f32_e32 v106, 1.0, v106
	v_cmp_gt_f32_e32 vcc, s21, v106
	s_nop 1
	v_cndmask_b32_e64 v107, 0, 32, vcc
	v_ldexp_f32 v106, v106, v107
	v_log_f32_e32 v106, v106
	s_nop 0
	v_mul_f32_e32 v107, 0x3f317217, v106
	v_fma_f32 v107, v106, s20, -v107
	v_fmac_f32_e32 v107, 0x3377d1cf, v106
	v_fmac_f32_e32 v107, 0x3f317217, v106
	v_cmp_lt_f32_e64 s[70:71], |v106|, s19
	s_nop 1
	v_cndmask_b32_e64 v106, v106, v107, s[70:71]
	v_cndmask_b32_e32 v107, 0, v147, vcc
	v_cmp_gt_f32_e32 vcc, s21, v103
	v_sub_f32_e32 v119, v106, v107
	v_pk_add_f32 v[86:87], v[110:111], v[118:119] neg_lo:[0,1] neg_hi:[0,1]
	v_cndmask_b32_e64 v106, 0, 32, vcc
	v_ldexp_f32 v103, v103, v106
	v_log_f32_e32 v103, v103
	v_add_u32_e32 v119, s79, v170
	s_waitcnt vmcnt(8)
	v_lshlrev_b32_e32 v110, 16, v151
	v_and_b32_e32 v111, 0xffff0000, v151
	v_mul_f32_e32 v106, 0x3f317217, v103
	v_fma_f32 v106, v103, s20, -v106
	v_fmac_f32_e32 v106, 0x3377d1cf, v103
	v_fmac_f32_e32 v106, 0x3f317217, v103
	v_cmp_lt_f32_e64 s[70:71], |v103|, s19
	s_nop 1
	v_cndmask_b32_e64 v103, v103, v106, s[70:71]
	v_cndmask_b32_e32 v106, 0, v147, vcc
	v_cmp_gt_f32_e32 vcc, s21, v102
	v_sub_f32_e32 v122, v103, v106
	v_pk_fma_f32 v[106:107], v[84:85], s[78:79], v[82:83] op_sel_hi:[1,0,1]
	v_cndmask_b32_e64 v103, 0, 32, vcc
	v_ldexp_f32 v102, v102, v103
	v_log_f32_e32 v102, v102
	v_pk_add_f32 v[84:85], v[94:95], v[96:97] neg_lo:[0,1] neg_hi:[0,1]
	v_mul_f32_e32 v103, 0x3f317217, v102
	v_fma_f32 v103, v102, s20, -v103
	v_fmac_f32_e32 v103, 0x3377d1cf, v102
	v_fmac_f32_e32 v103, 0x3f317217, v102
	v_cmp_lt_f32_e64 s[70:71], |v102|, s19
	s_nop 1
	v_cndmask_b32_e64 v102, v102, v103, s[70:71]
	v_cndmask_b32_e32 v103, 0, v147, vcc
	v_sub_f32_e32 v123, v102, v103
	v_pk_fma_f32 v[102:103], v[84:85], s[78:79], v[106:107] op_sel_hi:[1,0,1]
	v_pk_add_f32 v[84:85], v[98:99], v[100:101] neg_lo:[0,1] neg_hi:[0,1]
	s_andn2_b64 vcc, exec, s[84:85]
	v_pk_fma_f32 v[88:89], v[84:85], s[78:79], v[102:103] op_sel_hi:[1,0,1]
	v_pk_add_f32 v[84:85], v[104:105], v[108:109] neg_lo:[0,1] neg_hi:[0,1]
	v_lshlrev_b32_e32 v104, 16, v154
	v_pk_fma_f32 v[84:85], v[84:85], s[78:79], v[88:89] op_sel_hi:[1,0,1]
	v_and_b32_e32 v105, 0xffff0000, v154
	v_pk_fma_f32 v[92:93], v[86:87], s[78:79], v[84:85] op_sel_hi:[1,0,1]
	v_pk_add_f32 v[86:87], v[120:121], v[122:123] neg_lo:[0,1] neg_hi:[0,1]
	s_nop 0
	v_pk_fma_f32 v[90:91], v[86:87], s[78:79], v[92:93] op_sel_hi:[1,0,1]
	ds_write_b64 v168, v[90:91]
	s_waitcnt vmcnt(8)
	ds_write_b128 v174, v[4:7] offset:53248
	s_waitcnt vmcnt(8)
	ds_write_b128 v175, v[8:11] offset:53248
	s_waitcnt vmcnt(8)
	ds_write_b128 v176, v[12:15] offset:53248
	s_waitcnt vmcnt(8)
	ds_write_b128 v177, v[114:117] offset:53248
	s_waitcnt lgkmcnt(0)
	s_barrier
; __device__ __forceinline__ float bflo(unsigned w) { return __uint_as_float(w << 16); }
; __device__ __forceinline__ float bfhi(unsigned w) { return __uint_as_float(w & 0xffff0000u); }
; #define GLDS __attribute__((address_space(3)))
; __device__ __forceinline__ float bflo(unsigned w) { return __uint_as_float(w << 16); }
; __device__ __forceinline__ float bfhi(unsigned w) { return __uint_as_float(w & 0xffff0000u); }
; __device__ __forceinline__ unsigned pk(float lo, float hi) { typedef float f2 __attribute__((ext_vector_type(2))); typedef __bf16 b2 __attribute__((ext_vector_type(2))); f2 v = {lo, hi}; b2 b = __builtin_convertvector(v, b2); return __builtin_bit_cast(unsigned, b); }
; __device__ __forceinline__ unsigned pk(float lo, float hi) { return gla::pk(lo, hi); }
; template <int MODE> __device__ __forceinline__ void chain(int b, int h, int seg, float* __restrict__ SLOC, float* __restrict__ DTOT, const bf16_t* __restrict__ QB, const bf16_t* __restrict__ KB, const bf16_t* __restrict__ VB, bf16_t* __restrict__ OB, const bf16_t* __restrict__ RB, const float* __res ...
;     ...
;         {
;             float pre0 = 0.f, pre1 = 0.f, tot0 = 0.f, tot1 = 0.f;
; #pragma unroll
;             for (int w = 0; w < 8; ++w) { const f32x2 sg = *(const GLDS f32x2*)(SEG + w * 128 + c0); tot0 += sg.x; tot1 += sg.y; if (w < wid) { pre0 += sg.x; pre1 += sg.y; } }
;             unsigned kh0[4], kh1[4];
; #pragma unroll
;             for (int i = 0; i < 8; i += 2) {
;                 float kx0[2], kx1[2];
; #pragma unroll
;                 for (int d = 0; d < 2; ++d) { const int ii = i + d; const float b0 = pre0 + bl0[ii], b1 = pre1 + bl1[ii];
;                     const float qa = bflo(q2[ii]), qb = bfhi(q2[ii]), ka = bflo(k2[ii]), kb = bfhi(k2[ii]);
;                     if (MODE == 1) { *(GLDS unsigned*)(L + QT_OFF + (8 * wid + ii) * QT_RS + c0 * 2) = pk(qa * SCQ * __expf(b0), qb * SCQ * __expf(b1));
;                     *(GLDS unsigned*)(L + KT_OFF + (8 * wid + ii) * QT_RS + c0 * 2) = pk(ka * __expf(-b0), kb * __expf(-b1)); }
;                     kx0[d] = ka * __expf(tot0 - b0); kx1[d] = kb * __expf(tot1 - b1); }
;                 kh0[i >> 1] = pk(kx0[0], kx0[1]); kh1[i >> 1] = pk(kx1[0], kx1[1]);
;             }
	ds_read2st64_b64 v[94:97], v169 offset1:1
	s_waitcnt lgkmcnt(0)
	v_add_f32_e32 v86, 0, v94
	v_add_f32_e32 v87, 0, v95
	v_cndmask_b32_e64 v94, v87, 0, s[84:85]
	v_cndmask_b32_e64 v95, v86, 0, s[84:85]
	v_add_f32_e32 v86, v86, v96
	v_add_f32_e32 v87, v87, v97
	v_add_f32_e32 v96, v96, v95
	v_add_f32_e32 v97, v97, v94
	v_cndmask_b32_e64 v98, v94, v97, s[38:39]
	v_cndmask_b32_e64 v99, v95, v96, s[38:39]
	ds_read2st64_b64 v[94:97], v169 offset0:2 offset1:3
	s_waitcnt lgkmcnt(0)
	v_add_f32_e32 v86, v86, v94
	v_add_f32_e32 v87, v87, v95
	v_add_f32_e32 v94, v94, v99
	v_add_f32_e32 v95, v95, v98
	v_cndmask_b32_e64 v95, v98, v95, s[40:41]
	v_cndmask_b32_e64 v94, v99, v94, s[40:41]
	v_add_f32_e32 v86, v86, v96
	v_add_f32_e32 v87, v87, v97
	v_add_f32_e32 v96, v96, v94
	v_add_f32_e32 v97, v97, v95
	v_cndmask_b32_e64 v98, v95, v97, s[42:43]
	v_cndmask_b32_e64 v99, v94, v96, s[42:43]
	ds_read2st64_b64 v[94:97], v169 offset0:4 offset1:5
	s_waitcnt lgkmcnt(0)
	v_add_f32_e32 v86, v86, v94
	v_add_f32_e32 v87, v87, v95
	v_add_f32_e32 v94, v94, v99
	v_add_f32_e32 v95, v95, v98
	v_cndmask_b32_e64 v95, v98, v95, s[44:45]
	v_cndmask_b32_e64 v94, v99, v94, s[44:45]
	v_add_f32_e32 v86, v86, v96
	v_add_f32_e32 v87, v87, v97
	v_add_f32_e32 v96, v96, v94
	v_add_f32_e32 v97, v97, v95
	v_cndmask_b32_e64 v99, v95, v97, s[46:47]
	v_cndmask_b32_e64 v101, v94, v96, s[46:47]
	ds_read2st64_b64 v[94:97], v169 offset0:6 offset1:7
	s_waitcnt lgkmcnt(0)
	v_add_f32_e32 v100, v86, v94
	v_add_f32_e32 v98, v87, v95
	v_add_f32_e32 v86, v94, v101
	v_add_f32_e32 v87, v95, v99
	v_cndmask_b32_e64 v87, v99, v87, s[48:49]
	v_cndmask_b32_e64 v86, v101, v86, s[48:49]
	v_add_f32_e32 v94, v96, v86
	v_add_f32_e32 v95, v97, v87
	v_cndmask_b32_e64 v99, v87, v95, s[50:51]
	v_cndmask_b32_e64 v101, v86, v94, s[50:51]
	v_add_f32_e32 v108, v112, v101
	v_add_f32_e32 v109, v113, v99
	v_mul_f32_e32 v94, 0x3fb8aa3b, v108
	v_mul_f32_e32 v95, 0x3fb8aa3b, v109
	v_exp_f32_e32 v94, v94
	v_exp_f32_e32 v95, v95
	v_lshlrev_b32_e32 v86, 16, v148
	v_and_b32_e32 v87, 0xffff0000, v148
	v_pk_mul_f32 v[86:87], v[86:87], s[80:81] op_sel_hi:[1,0]
	s_nop 0
	v_pk_mul_f32 v[86:87], v[86:87], v[94:95]
	s_nop 0
	v_cvt_pk_bf16_f32 v118, v86, v87
	v_mul_f32_e32 v86, 0xbfb8aa3b, v108
	v_mul_f32_e32 v87, 0xbfb8aa3b, v109
	v_exp_f32_e32 v86, v86
	v_exp_f32_e32 v87, v87
	s_nop 0
	v_pk_mul_f32 v[86:87], v[86:87], v[104:105]
	s_nop 0
	v_cvt_pk_bf16_f32 v120, v86, v87
	v_mov_b32_e32 v86, v96
	v_mov_b32_e32 v87, v82
	v_pk_add_f32 v[94:95], v[100:101], v[86:87]
	s_nop 0
	v_sub_f32_e32 v82, v94, v108
	v_mul_f32_e32 v82, 0x3fb8aa3b, v82
	v_exp_f32_e32 v86, v82
	v_mov_b32_e32 v82, v97
	v_pk_add_f32 v[96:97], v[98:99], v[82:83]
	v_mul_f32_e32 v83, 0x3fb8aa3b, v95
	v_exp_f32_e32 v112, v83
	v_mul_f32_e32 v83, 0x3fb8aa3b, v97
	v_exp_f32_e32 v113, v83
	v_sub_f32_e32 v82, v96, v109
	v_lshlrev_b32_e32 v108, 16, v139
	v_and_b32_e32 v109, 0xffff0000, v139
	v_pk_mul_f32 v[108:109], v[108:109], s[80:81] op_sel_hi:[1,0]
	v_add_u32_e32 v98, 0x4400, v119
	v_pk_mul_f32 v[108:109], v[108:109], v[112:113]
	v_mul_f32_e32 v82, 0x3fb8aa3b, v82
	v_cvt_pk_bf16_f32 v83, v108, v109
	ds_write2_b32 v119, v118, v83 offset1:68
	v_mul_f32_e32 v83, 0xbfb8aa3b, v95
	v_exp_f32_e32 v108, v83
	v_mul_f32_e32 v83, 0xbfb8aa3b, v97
	v_exp_f32_e32 v109, v83
	v_exp_f32_e32 v82, v82
	v_pk_mul_f32 v[108:109], v[108:109], v[110:111]
	s_nop 0
	v_cvt_pk_bf16_f32 v83, v108, v109
	ds_write2_b32 v98, v120, v83 offset1:68
	v_sub_f32_e32 v83, v94, v95
	v_mul_f32_e32 v83, 0x3fb8aa3b, v83
	v_exp_f32_e32 v87, v83
	v_sub_f32_e32 v83, v96, v97
	v_mul_f32_e32 v83, 0x3fb8aa3b, v83
	v_exp_f32_e32 v83, v83
	v_mov_b32_e32 v109, v110
	v_mov_b32_e32 v110, v105
	v_mov_b32_e32 v108, v104
	v_pk_mul_f32 v[82:83], v[82:83], v[110:111]
	v_pk_mul_f32 v[86:87], v[86:87], v[108:109]
	v_cvt_pk_bf16_f32 v82, v82, v83
	v_add_f32_e32 v83, v106, v101
	v_cvt_pk_bf16_f32 v86, v86, v87
	v_add_f32_e32 v87, v107, v99
	v_mul_f32_e32 v95, 0x3fb8aa3b, v83
	v_exp_f32_e32 v108, v95
	v_mul_f32_e32 v95, 0x3fb8aa3b, v87
	v_exp_f32_e32 v109, v95
	v_lshlrev_b32_e32 v104, 16, v149
	v_and_b32_e32 v105, 0xffff0000, v149
	v_pk_mul_f32 v[104:105], v[104:105], s[80:81] op_sel_hi:[1,0]
	v_mul_f32_e32 v97, 0xbfb8aa3b, v83
	v_pk_mul_f32 v[104:105], v[104:105], v[108:109]
	v_lshlrev_b32_e32 v106, 16, v152
	v_cvt_pk_bf16_f32 v95, v104, v105
	v_exp_f32_e32 v104, v97
	v_mul_f32_e32 v97, 0xbfb8aa3b, v87
	v_exp_f32_e32 v105, v97
	v_and_b32_e32 v107, 0xffff0000, v152
	v_sub_f32_e32 v83, v94, v83
	v_mul_f32_e32 v83, 0x3fb8aa3b, v83
	v_pk_mul_f32 v[104:105], v[104:105], v[106:107]
	v_lshlrev_b32_e32 v110, 16, v153
	v_cvt_pk_bf16_f32 v97, v104, v105
	v_exp_f32_e32 v104, v83
	v_sub_f32_e32 v83, v96, v87
	v_mul_f32_e32 v83, 0x3fb8aa3b, v83
	v_exp_f32_e32 v108, v83
	v_add_f32_e32 v83, v102, v101
	v_add_f32_e32 v87, v103, v99
	v_mul_f32_e32 v100, 0x3fb8aa3b, v83
	v_exp_f32_e32 v112, v100
	v_mul_f32_e32 v100, 0x3fb8aa3b, v87
	v_exp_f32_e32 v113, v100
	v_lshlrev_b32_e32 v102, 16, v150
	v_and_b32_e32 v103, 0xffff0000, v150
	v_pk_mul_f32 v[102:103], v[102:103], s[80:81] op_sel_hi:[1,0]
	v_and_b32_e32 v111, 0xffff0000, v153
	v_pk_mul_f32 v[102:103], v[102:103], v[112:113]
	s_nop 0
	v_cvt_pk_bf16_f32 v100, v102, v103
	ds_write2_b32 v119, v95, v100 offset0:136 offset1:204
	v_mul_f32_e32 v95, 0xbfb8aa3b, v83
	v_exp_f32_e32 v102, v95
	v_mul_f32_e32 v95, 0xbfb8aa3b, v87
	v_sub_f32_e32 v83, v94, v83
	v_exp_f32_e32 v103, v95
	v_mul_f32_e32 v83, 0x3fb8aa3b, v83
	v_exp_f32_e32 v105, v83
	v_sub_f32_e32 v83, v96, v87
	v_mul_f32_e32 v83, 0x3fb8aa3b, v83
	v_exp_f32_e32 v109, v83
	v_pk_mul_f32 v[102:103], v[102:103], v[110:111]
	s_nop 0
	v_cvt_pk_bf16_f32 v95, v102, v103
; __device__ __forceinline__ float bflo(unsigned w) { return __uint_as_float(w << 16); }
; __device__ __forceinline__ float bfhi(unsigned w) { return __uint_as_float(w & 0xffff0000u); }
; #define GLDS __attribute__((address_space(3)))
; __device__ __forceinline__ float bflo(unsigned w) { return __uint_as_float(w << 16); }
; __device__ __forceinline__ float bfhi(unsigned w) { return __uint_as_float(w & 0xffff0000u); }
; __device__ __forceinline__ unsigned pk(float lo, float hi) { typedef float f2 __attribute__((ext_vector_type(2))); typedef __bf16 b2 __attribute__((ext_vector_type(2))); f2 v = {lo, hi}; b2 b = __builtin_convertvector(v, b2); return __builtin_bit_cast(unsigned, b); }
; __device__ __forceinline__ unsigned pk(float lo, float hi) { return gla::pk(lo, hi); }
; template <int MODE> __device__ __forceinline__ void chain(int b, int h, int seg, float* __restrict__ SLOC, float* __restrict__ DTOT, const bf16_t* __restrict__ QB, const bf16_t* __restrict__ KB, const bf16_t* __restrict__ VB, bf16_t* __restrict__ OB, const bf16_t* __restrict__ RB, const float* __res ...
;     ...
;             for (int i = 0; i < 8; i += 2) {
;                 float kx0[2], kx1[2];
; #pragma unroll
;                 for (int d = 0; d < 2; ++d) { const int ii = i + d; const float b0 = pre0 + bl0[ii], b1 = pre1 + bl1[ii];
;                     const float qa = bflo(q2[ii]), qb = bfhi(q2[ii]), ka = bflo(k2[ii]), kb = bfhi(k2[ii]);
;                     if (MODE == 1) { *(GLDS unsigned*)(L + QT_OFF + (8 * wid + ii) * QT_RS + c0 * 2) = pk(qa * SCQ * __expf(b0), qb * SCQ * __expf(b1));
;                     *(GLDS unsigned*)(L + KT_OFF + (8 * wid + ii) * QT_RS + c0 * 2) = pk(ka * __expf(-b0), kb * __expf(-b1)); }
;                     kx0[d] = ka * __expf(tot0 - b0); kx1[d] = kb * __expf(tot1 - b1); }
;                 kh0[i >> 1] = pk(kx0[0], kx0[1]); kh1[i >> 1] = pk(kx1[0], kx1[1]);
;             }
;             *(GLDS u32x4*)(L + KH_OFF + c0 * KH_RS + wid * 16) = (u32x4){kh0[0], kh0[1], kh0[2], kh0[3]};
;             *(GLDS u32x4*)(L + KH_OFF + (c0 + 1) * KH_RS + wid * 16) = (u32x4){kh1[0], kh1[1], kh1[2], kh1[3]};
;             if (wid == 0) *(GLDS f32x2*)(EBL + c0) = (f32x2){__expf(tot0), __expf(tot1)};
	ds_write2_b32 v98, v97, v95 offset0:136 offset1:204
	v_mov_b32_e32 v102, v106
	v_mov_b32_e32 v103, v110
	v_mov_b32_e32 v110, v107
	v_add_f32_e32 v95, v88, v101
	v_pk_mul_f32 v[102:103], v[104:105], v[102:103]
	v_pk_mul_f32 v[104:105], v[108:109], v[110:111]
	v_add_f32_e32 v97, v89, v99
	v_mul_f32_e32 v98, 0x3fb8aa3b, v95
	v_cvt_pk_bf16_f32 v83, v104, v105
	v_exp_f32_e32 v104, v98
	v_mul_f32_e32 v98, 0x3fb8aa3b, v97
	v_exp_f32_e32 v105, v98
	v_lshlrev_b32_e32 v88, 16, v155
	v_and_b32_e32 v89, 0xffff0000, v155
	v_pk_mul_f32 v[88:89], v[88:89], s[80:81] op_sel_hi:[1,0]
	v_cvt_pk_bf16_f32 v87, v102, v103
	v_pk_mul_f32 v[88:89], v[88:89], v[104:105]
	v_lshlrev_b32_e32 v102, 16, v159
	v_cvt_pk_bf16_f32 v98, v88, v89
	v_mul_f32_e32 v88, 0xbfb8aa3b, v95
	v_mul_f32_e32 v89, 0xbfb8aa3b, v97
	v_exp_f32_e32 v88, v88
	v_exp_f32_e32 v89, v89
	v_and_b32_e32 v103, 0xffff0000, v159
	v_lshlrev_b32_e32 v106, 16, v160
	v_and_b32_e32 v107, 0xffff0000, v160
	v_pk_mul_f32 v[88:89], v[88:89], v[102:103]
	s_nop 0
	v_cvt_pk_bf16_f32 v89, v88, v89
	v_sub_f32_e32 v88, v94, v95
	v_sub_f32_e32 v95, v96, v97
	v_mul_f32_e32 v95, 0x3fb8aa3b, v95
	v_exp_f32_e32 v104, v95
	v_add_f32_e32 v95, v84, v101
	v_add_f32_e32 v97, v85, v99
	v_mul_f32_e32 v100, 0x3fb8aa3b, v95
	v_exp_f32_e32 v108, v100
	v_mul_f32_e32 v100, 0x3fb8aa3b, v97
	v_exp_f32_e32 v109, v100
	v_lshlrev_b32_e32 v84, 16, v156
	v_and_b32_e32 v85, 0xffff0000, v156
	v_pk_mul_f32 v[84:85], v[84:85], s[80:81] op_sel_hi:[1,0]
	v_mul_f32_e32 v88, 0x3fb8aa3b, v88
	v_pk_mul_f32 v[84:85], v[84:85], v[108:109]
	v_add_u32_e32 v108, 0x400, v119
	v_cvt_pk_bf16_f32 v84, v84, v85
	ds_write2_b32 v108, v98, v84 offset0:16 offset1:84
	v_mul_f32_e32 v84, 0xbfb8aa3b, v95
	v_mul_f32_e32 v85, 0xbfb8aa3b, v97
	v_exp_f32_e32 v84, v84
	v_exp_f32_e32 v85, v85
	v_add_u32_e32 v109, 0x4800, v119
	v_exp_f32_e32 v88, v88
	v_lshlrev_b32_e32 v100, 16, v162
	v_pk_mul_f32 v[84:85], v[84:85], v[106:107]
	s_nop 0
	v_cvt_pk_bf16_f32 v84, v84, v85
	ds_write2_b32 v109, v89, v84 offset0:16 offset1:84
	v_sub_f32_e32 v84, v94, v95
	v_mul_f32_e32 v84, 0x3fb8aa3b, v84
	v_exp_f32_e32 v89, v84
	v_mov_b32_e32 v84, v102
	v_mov_b32_e32 v85, v106
	v_mov_b32_e32 v106, v103
	v_pk_mul_f32 v[84:85], v[88:89], v[84:85]
	v_sub_f32_e32 v88, v96, v97
	v_mul_f32_e32 v88, 0x3fb8aa3b, v88
	v_exp_f32_e32 v105, v88
	v_cvt_pk_bf16_f32 v88, v84, v85
	v_add_f32_e32 v85, v92, v101
	v_add_f32_e32 v89, v93, v99
	v_mul_f32_e32 v95, 0x3fb8aa3b, v85
	v_pk_mul_f32 v[102:103], v[104:105], v[106:107]
	v_exp_f32_e32 v104, v95
	v_mul_f32_e32 v95, 0x3fb8aa3b, v89
	v_exp_f32_e32 v105, v95
	v_lshlrev_b32_e32 v92, 16, v157
	v_and_b32_e32 v93, 0xffff0000, v157
	v_pk_mul_f32 v[92:93], v[92:93], s[80:81] op_sel_hi:[1,0]
	v_cvt_pk_bf16_f32 v84, v102, v103
	v_pk_mul_f32 v[92:93], v[92:93], v[104:105]
	v_lshlrev_b32_e32 v102, 16, v161
	v_cvt_pk_bf16_f32 v95, v92, v93
	v_mul_f32_e32 v92, 0xbfb8aa3b, v85
	v_mul_f32_e32 v93, 0xbfb8aa3b, v89
	v_exp_f32_e32 v92, v92
	v_exp_f32_e32 v93, v93
	v_and_b32_e32 v103, 0xffff0000, v161
	v_sub_f32_e32 v85, v94, v85
	v_mul_f32_e32 v85, 0x3fb8aa3b, v85
	v_pk_mul_f32 v[92:93], v[92:93], v[102:103]
	s_nop 0
	v_cvt_pk_bf16_f32 v93, v92, v93
	v_exp_f32_e32 v92, v85
	v_sub_f32_e32 v85, v96, v89
	v_mul_f32_e32 v85, 0x3fb8aa3b, v85
	v_exp_f32_e32 v98, v85
	v_add_f32_e32 v85, v90, v101
	v_add_f32_e32 v89, v91, v99
	v_mul_f32_e32 v97, 0x3fb8aa3b, v85
	v_exp_f32_e32 v104, v97
	v_mul_f32_e32 v97, 0x3fb8aa3b, v89
	v_exp_f32_e32 v105, v97
	v_lshlrev_b32_e32 v90, 16, v158
	v_and_b32_e32 v91, 0xffff0000, v158
	v_pk_mul_f32 v[90:91], v[90:91], s[80:81] op_sel_hi:[1,0]
	v_and_b32_e32 v101, 0xffff0000, v162
	v_pk_mul_f32 v[90:91], v[90:91], v[104:105]
	s_nop 0
	v_cvt_pk_bf16_f32 v90, v90, v91
	ds_write2_b32 v108, v95, v90 offset0:152 offset1:220
	v_mul_f32_e32 v90, 0xbfb8aa3b, v85
	v_mul_f32_e32 v91, 0xbfb8aa3b, v89
	v_exp_f32_e32 v90, v90
	v_exp_f32_e32 v91, v91
	v_sub_f32_e32 v85, v94, v85
	v_mul_f32_e32 v85, 0x3fb8aa3b, v85
	v_pk_mul_f32 v[90:91], v[90:91], v[100:101]
	s_nop 0
	v_cvt_pk_bf16_f32 v90, v90, v91
	ds_write2_b32 v109, v93, v90 offset0:152 offset1:220
	v_exp_f32_e32 v93, v85
	v_sub_f32_e32 v85, v96, v89
	v_mul_f32_e32 v85, 0x3fb8aa3b, v85
	v_exp_f32_e32 v99, v85
	v_mov_b32_e32 v90, v102
	v_mov_b32_e32 v91, v100
	v_pk_mul_f32 v[90:91], v[92:93], v[90:91]
	v_mov_b32_e32 v100, v103
	v_pk_mul_f32 v[92:93], v[98:99], v[100:101]
	v_cvt_pk_bf16_f32 v89, v90, v91
	v_cvt_pk_bf16_f32 v85, v92, v93
	ds_write_b128 v178, v[86:89] offset:34816
	ds_write_b128 v178, v[82:85] offset:34960
	s_cbranch_vccnz .LBB0_676
	v_mul_f32_e32 v82, 0x3fb8aa3b, v94
	v_mul_f32_e32 v83, 0x3fb8aa3b, v96
	v_exp_f32_e32 v82, v82
	v_exp_f32_e32 v83, v83
	ds_write_b64 v171, v[82:83]
; template <int MODE> __device__ __forceinline__ void chain(int b, int h, int seg, float* __restrict__ SLOC, float* __restrict__ DTOT, const bf16_t* __restrict__ QB, const bf16_t* __restrict__ KB, const bf16_t* __restrict__ VB, bf16_t* __restrict__ OB, const bf16_t* __restrict__ RB, const float* __res ...
;     ...
;         if (n + 1 < 16) GLA_LOAD(row0 + 64);
.LBB0_676:
	s_waitcnt lgkmcnt(0)
	s_barrier
	v_lshl_add_u64 v[118:119], v[16:17], 0, s[82:83]
	s_mov_b32 s4, 0x27700000
	v_add_co_u32_e32 v120, vcc, s4, v118
	s_mov_b32 s4, 0x27710000
	s_nop 0
	v_addc_co_u32_e32 v121, vcc, 0, v119, vcc
	v_add_co_u32_e32 v118, vcc, s4, v118
	global_load_dwordx2 v[218:219], v[120:121], off
	global_load_dwordx2 v[220:221], v[120:121], off offset:16
	global_load_dwordx2 v[222:223], v[120:121], off offset:32
	global_load_dwordx2 v[224:225], v[120:121], off offset:48
	v_addc_co_u32_e32 v119, vcc, 0, v119, vcc
	global_load_dwordx2 v[226:227], v[118:119], off
	global_load_dwordx2 v[228:229], v[118:119], off offset:16
	global_load_dwordx2 v[230:231], v[118:119], off offset:32
	s_nop 0
	global_load_dwordx2 v[232:233], v[118:119], off offset:48
	s_cmp_eq_u32 s82, 0x1e0000
	s_cbranch_scc1 .LBB0_678
	v_lshl_add_u64 v[122:123], s[74:75], 0, v[2:3]
	v_add_co_u32_e32 v122, vcc, 0x2801000, v122
	s_nop 1
	v_addc_co_u32_e32 v123, vcc, 0, v123, vcc
	global_load_dword v165, v[122:123], off
	global_load_dword v166, v[122:123], off offset:256
	v_lshl_add_u64 v[124:125], v[142:143], 0, s[82:83]
	v_add_co_u32_e32 v126, vcc, 0x1f620000, v124
	s_nop 1
	v_addc_co_u32_e32 v127, vcc, 0, v125, vcc
	v_add_co_u32_e32 v128, vcc, 0x1f628000, v124
	s_nop 1
	v_addc_co_u32_e32 v129, vcc, 0, v125, vcc
	global_load_dwordx4 v[4:7], v[126:127], off
	global_load_dwordx4 v[8:11], v[128:129], off
	v_add_co_u32_e32 v126, vcc, 0x1f630000, v124
	s_nop 1
	v_addc_co_u32_e32 v127, vcc, 0, v125, vcc
	v_add_co_u32_e32 v128, vcc, 0x1f638000, v124
	s_nop 1
	v_addc_co_u32_e32 v129, vcc, 0, v125, vcc
	global_load_dwordx4 v[12:15], v[126:127], off
	global_load_dwordx4 v[114:117], v[128:129], off
	v_lshl_add_u64 v[122:123], s[76:77], 0, v[2:3]
	v_add_co_u32_e32 v124, vcc, 0x17410000, v122
	s_nop 1
	v_addc_co_u32_e32 v125, vcc, 0, v123, vcc
	v_add_co_u32_e32 v122, vcc, 0x17411000, v122
	s_nop 1
	v_addc_co_u32_e32 v123, vcc, 0, v123, vcc
	v_lshl_add_u64 v[126:127], s[6:7], 0, v[2:3]
	v_add_co_u32_e32 v128, vcc, 0x1b510000, v126
	s_nop 1
	v_addc_co_u32_e32 v129, vcc, 0, v127, vcc
	v_add_co_u32_e32 v126, vcc, 0x1b511000, v126
	s_nop 1
	v_addc_co_u32_e32 v127, vcc, 0, v127, vcc
	global_load_dword v148, v[124:125], off
	global_load_dword v139, v[124:125], off offset:1024
	global_load_dword v149, v[124:125], off offset:2048
	global_load_dword v150, v[124:125], off offset:3072
	global_load_dword v154, v[128:129], off
	global_load_dword v151, v[128:129], off offset:1024
	global_load_dword v152, v[128:129], off offset:2048
	global_load_dword v153, v[128:129], off offset:3072
	global_load_dword v155, v[122:123], off
	global_load_dword v156, v[122:123], off offset:1024
	global_load_dword v157, v[122:123], off offset:2048
	global_load_dword v158, v[122:123], off offset:3072
	global_load_dword v159, v[126:127], off
	global_load_dword v160, v[126:127], off offset:1024
	global_load_dword v161, v[126:127], off offset:2048
	global_load_dword v162, v[126:127], off offset:3072
